# PAPR 3-way split: workgroups 64..95 publish T of their first PA tile immediately (removes the consumer stall)
# speedup vs baseline: 1.0173x; 1.0057x over previous
.LBB0_1393:
	v_lshl_or_b32 v146, s30, 8, v157
	v_lshl_add_u32 v148, s52, 8, v129
	v_ashrrev_i32_e32 v147, 31, v146
	v_mov_b64_e32 v[150:151], s[8:9]
	v_mad_i64_i32 v[154:155], s[54:55], v148, s71, v[150:151]
	v_lshlrev_b64 v[152:153], 1, v[146:147]
	v_lshl_add_u64 v[154:155], v[154:155], 0, v[152:153]
	v_add_co_u32_e32 v162, vcc, 0x3000, v154
	v_or_b32_e32 v182, 16, v148
	s_nop 0
	v_addc_co_u32_e32 v163, vcc, 0, v155, vcc
	v_lshl_add_u64 v[154:155], v[154:155], 0, s[18:19]
	global_load_dwordx4 v[162:165], v[162:163], off offset:3072
	v_or_b32_e32 v194, 32, v148
	global_load_dwordx4 v[166:169], v[154:155], off offset:256
	v_mad_i64_i32 v[154:155], s[54:55], v182, s71, v[150:151]
	v_lshl_add_u64 v[154:155], v[154:155], 0, v[152:153]
	v_add_co_u32_e32 v170, vcc, s72, v154
	v_mad_i64_i32 v[178:179], s[54:55], v194, s71, v[150:151]
	s_nop 0
	v_addc_co_u32_e32 v171, vcc, 0, v155, vcc
	global_load_dwordx4 v[170:173], v[170:171], off offset:3072
	v_lshl_add_u64 v[154:155], v[154:155], 0, s[18:19]
	global_load_dwordx4 v[174:177], v[154:155], off offset:256
	v_lshl_add_u64 v[184:185], v[178:179], 0, v[152:153]
	v_add_co_u32_e32 v178, vcc, s72, v184
	v_ashrrev_i32_e32 v183, 31, v182
	s_nop 0
	v_addc_co_u32_e32 v179, vcc, 0, v185, vcc
	global_load_dwordx4 v[178:181], v[178:179], off offset:3072
	v_lshlrev_b64 v[196:197], 13, v[182:183]
	v_lshl_add_u64 v[182:183], v[184:185], 0, s[18:19]
	v_or_b32_e32 v154, 48, v148
	global_load_dwordx4 v[182:185], v[182:183], off offset:256
	v_mad_i64_i32 v[186:187], s[54:55], v154, s71, v[150:151]
	v_ashrrev_i32_e32 v149, 31, v148
	v_lshl_add_u64 v[186:187], v[186:187], 0, v[152:153]
	v_lshlrev_b64 v[188:189], 13, v[148:149]
	v_lshl_add_u64 v[190:191], v[186:187], 0, s[18:19]
	v_add_co_u32_e32 v186, vcc, s72, v186
	v_lshlrev_b64 v[146:147], 2, v[146:147]
	v_lshl_add_u64 v[188:189], s[6:7], 0, v[188:189]
	v_addc_co_u32_e32 v187, vcc, 0, v187, vcc
	v_lshl_add_u64 v[198:199], v[188:189], 0, v[146:147]
	global_load_dwordx4 v[186:189], v[186:187], off offset:3072
	s_nop 0
	global_load_dwordx4 v[190:193], v[190:191], off offset:256
	v_ashrrev_i32_e32 v195, 31, v194
	v_ashrrev_i32_e32 v155, 31, v154
	s_waitcnt vmcnt(0)
	v_lshlrev_b32_e32 v200, 16, v162
	v_and_b32_e32 v201, 0xffff0000, v162
	v_lshlrev_b32_e32 v162, 16, v163
	v_and_b32_e32 v163, 0xffff0000, v163
	v_lshlrev_b32_e32 v204, 16, v166
	v_and_b32_e32 v205, 0xffff0000, v166
	v_lshlrev_b32_e32 v202, 16, v164
	v_and_b32_e32 v203, 0xffff0000, v164
	v_lshlrev_b32_e32 v164, 16, v165
	v_and_b32_e32 v165, 0xffff0000, v165
	v_lshlrev_b32_e32 v166, 16, v167
	v_and_b32_e32 v167, 0xffff0000, v167
	v_lshlrev_b32_e32 v206, 16, v168
	v_and_b32_e32 v207, 0xffff0000, v168
	v_lshlrev_b32_e32 v168, 16, v169
	v_and_b32_e32 v169, 0xffff0000, v169
	v_pk_mul_f32 v[124:125], v[124:125], v[200:201]
	v_pk_mul_f32 v[126:127], v[126:127], v[162:163]
	v_pk_mul_f32 v[112:113], v[112:113], v[204:205]
	v_pk_mul_f32 v[120:121], v[120:121], v[202:203]
	v_pk_mul_f32 v[122:123], v[122:123], v[164:165]
	v_pk_mul_f32 v[114:115], v[114:115], v[166:167]
	v_pk_mul_f32 v[108:109], v[108:109], v[206:207]
	v_pk_mul_f32 v[110:111], v[110:111], v[168:169]
	global_store_dwordx4 v[198:199], v[124:127], off
	global_store_dwordx4 v[198:199], v[120:123], off offset:16
	global_store_dwordx4 v[198:199], v[112:115], off offset:512
	global_store_dwordx4 v[198:199], v[108:111], off offset:528
	s_nop 0
	v_lshlrev_b32_e32 v112, 16, v172
	v_and_b32_e32 v113, 0xffff0000, v172
	v_pk_mul_f32 v[104:105], v[104:105], v[112:113]
	v_lshlrev_b32_e32 v112, 16, v173
	v_and_b32_e32 v113, 0xffff0000, v173
	v_lshlrev_b32_e32 v108, 16, v170
	v_and_b32_e32 v109, 0xffff0000, v170
	v_lshlrev_b32_e32 v110, 16, v171
	v_and_b32_e32 v111, 0xffff0000, v171
	v_pk_mul_f32 v[106:107], v[106:107], v[112:113]
	v_lshl_add_u64 v[112:113], s[6:7], 0, v[196:197]
	v_pk_mul_f32 v[108:109], v[116:117], v[108:109]
	v_pk_mul_f32 v[110:111], v[118:119], v[110:111]
	v_lshl_add_u64 v[112:113], v[112:113], 0, v[146:147]
	global_store_dwordx4 v[112:113], v[108:111], off
	global_store_dwordx4 v[112:113], v[104:107], off offset:16
	s_nop 1
	v_lshlrev_b32_e32 v104, 16, v174
	v_and_b32_e32 v105, 0xffff0000, v174
	v_pk_mul_f32 v[100:101], v[100:101], v[104:105]
	v_lshlrev_b32_e32 v104, 16, v175
	v_and_b32_e32 v105, 0xffff0000, v175
	v_pk_mul_f32 v[102:103], v[102:103], v[104:105]
	v_lshlrev_b32_e32 v104, 16, v176
	v_and_b32_e32 v105, 0xffff0000, v176
	v_pk_mul_f32 v[92:93], v[92:93], v[104:105]
	v_lshlrev_b32_e32 v104, 16, v177
	v_and_b32_e32 v105, 0xffff0000, v177
	v_pk_mul_f32 v[94:95], v[94:95], v[104:105]
	global_store_dwordx4 v[112:113], v[100:103], off offset:512
	global_store_dwordx4 v[112:113], v[92:95], off offset:528
	s_nop 0
	v_lshlrev_b64 v[100:101], 13, v[194:195]
	v_lshlrev_b32_e32 v92, 16, v178
	v_and_b32_e32 v93, 0xffff0000, v178
	v_pk_mul_f32 v[92:93], v[96:97], v[92:93]
	v_lshlrev_b32_e32 v96, 16, v180
	v_and_b32_e32 v97, 0xffff0000, v180
	v_pk_mul_f32 v[88:89], v[88:89], v[96:97]
	v_lshlrev_b32_e32 v96, 16, v181
	v_and_b32_e32 v97, 0xffff0000, v181
	v_lshlrev_b32_e32 v94, 16, v179
	v_and_b32_e32 v95, 0xffff0000, v179
	v_pk_mul_f32 v[90:91], v[90:91], v[96:97]
	v_lshl_add_u64 v[96:97], s[6:7], 0, v[100:101]
	v_pk_mul_f32 v[94:95], v[98:99], v[94:95]
	v_lshl_add_u64 v[96:97], v[96:97], 0, v[146:147]
	global_store_dwordx4 v[96:97], v[92:95], off
	global_store_dwordx4 v[96:97], v[88:91], off offset:16
	v_add_u32_e32 v98, 0x90, v148
	v_add_u32_e32 v100, 0xa0, v148
	v_lshlrev_b32_e32 v88, 16, v182
	v_and_b32_e32 v89, 0xffff0000, v182
	v_pk_mul_f32 v[84:85], v[84:85], v[88:89]
	v_lshlrev_b32_e32 v88, 16, v183
	v_and_b32_e32 v89, 0xffff0000, v183
	v_pk_mul_f32 v[86:87], v[86:87], v[88:89]
	v_lshlrev_b32_e32 v88, 16, v184
	v_and_b32_e32 v89, 0xffff0000, v184
	v_pk_mul_f32 v[76:77], v[76:77], v[88:89]
	v_lshlrev_b32_e32 v88, 16, v185
	v_and_b32_e32 v89, 0xffff0000, v185
	v_pk_mul_f32 v[78:79], v[78:79], v[88:89]
	global_store_dwordx4 v[96:97], v[84:87], off offset:512
	global_store_dwordx4 v[96:97], v[76:79], off offset:528
	v_add_u32_e32 v96, 0x80, v148
	v_lshlrev_b64 v[84:85], 13, v[154:155]
	v_lshlrev_b32_e32 v76, 16, v186
	v_and_b32_e32 v77, 0xffff0000, v186
	v_pk_mul_f32 v[76:77], v[80:81], v[76:77]
	v_lshlrev_b32_e32 v80, 16, v188
	v_and_b32_e32 v81, 0xffff0000, v188
	v_pk_mul_f32 v[72:73], v[72:73], v[80:81]
	v_lshlrev_b32_e32 v80, 16, v189
	v_and_b32_e32 v81, 0xffff0000, v189
	v_lshlrev_b32_e32 v78, 16, v187
	v_and_b32_e32 v79, 0xffff0000, v187
	v_pk_mul_f32 v[74:75], v[74:75], v[80:81]
	v_lshl_add_u64 v[80:81], s[6:7], 0, v[84:85]
	v_pk_mul_f32 v[78:79], v[82:83], v[78:79]
	v_lshl_add_u64 v[80:81], v[80:81], 0, v[146:147]
	global_store_dwordx4 v[80:81], v[76:79], off
	global_store_dwordx4 v[80:81], v[72:75], off offset:16
	v_add_u32_e32 v102, 0xb0, v148
	v_ashrrev_i32_e32 v97, 31, v96
	v_lshlrev_b32_e32 v72, 16, v190
	v_and_b32_e32 v73, 0xffff0000, v190
	v_pk_mul_f32 v[68:69], v[68:69], v[72:73]
	v_lshlrev_b32_e32 v72, 16, v191
	v_and_b32_e32 v73, 0xffff0000, v191
	v_pk_mul_f32 v[70:71], v[70:71], v[72:73]
	v_lshlrev_b32_e32 v72, 16, v192
	v_and_b32_e32 v73, 0xffff0000, v192
	v_pk_mul_f32 v[64:65], v[64:65], v[72:73]
	v_lshlrev_b32_e32 v72, 16, v193
	v_and_b32_e32 v73, 0xffff0000, v193
	v_pk_mul_f32 v[66:67], v[66:67], v[72:73]
	global_store_dwordx4 v[80:81], v[68:71], off offset:512
	global_store_dwordx4 v[80:81], v[64:67], off offset:528
	v_ashrrev_i32_e32 v99, 31, v98
	v_ashrrev_i32_e32 v101, 31, v100
	v_mad_i64_i32 v[64:65], s[54:55], v96, s71, v[150:151]
	v_lshl_add_u64 v[64:65], v[64:65], 0, v[152:153]
	v_add_co_u32_e32 v66, vcc, s72, v64
	v_lshlrev_b64 v[96:97], 13, v[96:97]
	s_nop 0
	v_addc_co_u32_e32 v67, vcc, 0, v65, vcc
	global_load_dwordx4 v[68:71], v[66:67], off offset:3072
	v_lshl_add_u64 v[64:65], v[64:65], 0, s[18:19]
	global_load_dwordx4 v[72:75], v[64:65], off offset:256
	v_mad_i64_i32 v[64:65], s[54:55], v98, s71, v[150:151]
	v_lshl_add_u64 v[64:65], v[64:65], 0, v[152:153]
	v_add_co_u32_e32 v66, vcc, s72, v64
	v_ashrrev_i32_e32 v103, 31, v102
	s_nop 0
	v_addc_co_u32_e32 v67, vcc, 0, v65, vcc
	global_load_dwordx4 v[76:79], v[66:67], off offset:3072
	v_lshl_add_u64 v[64:65], v[64:65], 0, s[18:19]
	global_load_dwordx4 v[80:83], v[64:65], off offset:256
	v_mad_i64_i32 v[64:65], s[54:55], v100, s71, v[150:151]
	v_lshl_add_u64 v[64:65], v[64:65], 0, v[152:153]
	v_add_co_u32_e32 v66, vcc, s72, v64
	s_waitcnt vmcnt(3)
	v_lshlrev_b32_e32 v104, 16, v68
	v_addc_co_u32_e32 v67, vcc, 0, v65, vcc
	global_load_dwordx4 v[84:87], v[66:67], off offset:3072
	v_lshl_add_u64 v[64:65], v[64:65], 0, s[18:19]
	global_load_dwordx4 v[88:91], v[64:65], off offset:256
	v_mad_i64_i32 v[64:65], s[54:55], v102, s71, v[150:151]
	v_lshl_add_u64 v[64:65], v[64:65], 0, v[152:153]
	v_lshl_add_u64 v[66:67], v[64:65], 0, s[18:19]
	v_add_co_u32_e32 v64, vcc, s72, v64
	v_and_b32_e32 v105, 0xffff0000, v68
	s_nop 0
	v_addc_co_u32_e32 v65, vcc, 0, v65, vcc
	global_load_dwordx4 v[92:95], v[64:65], off offset:3072
	s_nop 0
	global_load_dwordx4 v[64:67], v[66:67], off offset:256
	v_lshlrev_b32_e32 v68, 16, v69
	v_and_b32_e32 v69, 0xffff0000, v69
	v_pk_mul_f32 v[62:63], v[62:63], v[68:69]
	v_lshlrev_b32_e32 v68, 16, v70
	v_and_b32_e32 v69, 0xffff0000, v70
	v_pk_mul_f32 v[56:57], v[56:57], v[68:69]
	v_lshlrev_b32_e32 v68, 16, v71
	v_and_b32_e32 v69, 0xffff0000, v71
	v_pk_mul_f32 v[58:59], v[58:59], v[68:69]
	v_lshl_add_u64 v[68:69], s[6:7], 0, v[96:97]
	v_pk_mul_f32 v[60:61], v[60:61], v[104:105]
	v_lshl_add_u64 v[68:69], v[68:69], 0, v[146:147]
	global_store_dwordx4 v[68:69], v[60:63], off
	global_store_dwordx4 v[68:69], v[56:59], off offset:16
	s_andn2_b64 vcc, exec, s[4:5]
	s_mov_b64 s[4:5], -1
	s_waitcnt vmcnt(8)
	v_lshlrev_b32_e32 v56, 16, v72
	v_and_b32_e32 v57, 0xffff0000, v72
	v_pk_mul_f32 v[52:53], v[52:53], v[56:57]
	v_lshlrev_b32_e32 v56, 16, v73
	v_and_b32_e32 v57, 0xffff0000, v73
	v_pk_mul_f32 v[54:55], v[54:55], v[56:57]
	v_lshlrev_b32_e32 v56, 16, v74
	v_and_b32_e32 v57, 0xffff0000, v74
	v_pk_mul_f32 v[44:45], v[44:45], v[56:57]
	v_lshlrev_b32_e32 v56, 16, v75
	v_and_b32_e32 v57, 0xffff0000, v75
	v_pk_mul_f32 v[46:47], v[46:47], v[56:57]
	global_store_dwordx4 v[68:69], v[52:55], off offset:512
	global_store_dwordx4 v[68:69], v[44:47], off offset:528
	s_nop 0
	v_lshlrev_b64 v[52:53], 13, v[98:99]
	s_waitcnt vmcnt(9)
	v_lshlrev_b32_e32 v44, 16, v76
	v_and_b32_e32 v45, 0xffff0000, v76
	v_pk_mul_f32 v[44:45], v[48:49], v[44:45]
	v_lshlrev_b32_e32 v48, 16, v78
	v_and_b32_e32 v49, 0xffff0000, v78
	v_pk_mul_f32 v[40:41], v[40:41], v[48:49]
	v_lshlrev_b32_e32 v48, 16, v79
	v_and_b32_e32 v49, 0xffff0000, v79
	v_lshlrev_b32_e32 v46, 16, v77
	v_and_b32_e32 v47, 0xffff0000, v77
	v_pk_mul_f32 v[42:43], v[42:43], v[48:49]
	v_lshl_add_u64 v[48:49], s[6:7], 0, v[52:53]
	v_pk_mul_f32 v[46:47], v[50:51], v[46:47]
	v_lshl_add_u64 v[48:49], v[48:49], 0, v[146:147]
	global_store_dwordx4 v[48:49], v[44:47], off
	global_store_dwordx4 v[48:49], v[40:43], off offset:16
	s_waitcnt vmcnt(10)
	s_nop 0
	v_lshlrev_b32_e32 v40, 16, v80
	v_and_b32_e32 v41, 0xffff0000, v80
	v_pk_mul_f32 v[36:37], v[36:37], v[40:41]
	v_lshlrev_b32_e32 v40, 16, v81
	v_and_b32_e32 v41, 0xffff0000, v81
	v_pk_mul_f32 v[38:39], v[38:39], v[40:41]
	v_lshlrev_b32_e32 v40, 16, v82
	v_and_b32_e32 v41, 0xffff0000, v82
	v_pk_mul_f32 v[28:29], v[28:29], v[40:41]
	v_lshlrev_b32_e32 v40, 16, v83
	v_and_b32_e32 v41, 0xffff0000, v83
	v_pk_mul_f32 v[30:31], v[30:31], v[40:41]
	global_store_dwordx4 v[48:49], v[36:39], off offset:512
	global_store_dwordx4 v[48:49], v[28:31], off offset:528
	s_nop 0
	v_lshlrev_b64 v[36:37], 13, v[100:101]
	s_waitcnt vmcnt(11)
	v_lshlrev_b32_e32 v28, 16, v84
	v_and_b32_e32 v29, 0xffff0000, v84
	v_pk_mul_f32 v[28:29], v[32:33], v[28:29]
	v_lshlrev_b32_e32 v32, 16, v86
	v_and_b32_e32 v33, 0xffff0000, v86
	v_pk_mul_f32 v[24:25], v[24:25], v[32:33]
	v_lshlrev_b32_e32 v32, 16, v87
	v_and_b32_e32 v33, 0xffff0000, v87
	v_lshlrev_b32_e32 v30, 16, v85
	v_and_b32_e32 v31, 0xffff0000, v85
	v_pk_mul_f32 v[26:27], v[26:27], v[32:33]
	v_lshl_add_u64 v[32:33], s[6:7], 0, v[36:37]
	v_pk_mul_f32 v[30:31], v[34:35], v[30:31]
	v_lshl_add_u64 v[32:33], v[32:33], 0, v[146:147]
	global_store_dwordx4 v[32:33], v[28:31], off
	global_store_dwordx4 v[32:33], v[24:27], off offset:16
	s_waitcnt vmcnt(12)
	s_nop 0
	v_lshlrev_b32_e32 v24, 16, v88
	v_and_b32_e32 v25, 0xffff0000, v88
	v_pk_mul_f32 v[20:21], v[20:21], v[24:25]
	v_lshlrev_b32_e32 v24, 16, v89
	v_and_b32_e32 v25, 0xffff0000, v89
	v_pk_mul_f32 v[22:23], v[22:23], v[24:25]
	v_lshlrev_b32_e32 v24, 16, v90
	v_and_b32_e32 v25, 0xffff0000, v90
	v_pk_mul_f32 v[12:13], v[12:13], v[24:25]
	v_lshlrev_b32_e32 v24, 16, v91
	v_and_b32_e32 v25, 0xffff0000, v91
	v_pk_mul_f32 v[14:15], v[14:15], v[24:25]
	global_store_dwordx4 v[32:33], v[20:23], off offset:512
	global_store_dwordx4 v[32:33], v[12:15], off offset:528
	s_nop 0
	v_lshlrev_b64 v[20:21], 13, v[102:103]
	s_waitcnt vmcnt(13)
	v_lshlrev_b32_e32 v12, 16, v92
	v_and_b32_e32 v13, 0xffff0000, v92
	v_pk_mul_f32 v[12:13], v[16:17], v[12:13]
	v_lshlrev_b32_e32 v16, 16, v94
	v_and_b32_e32 v17, 0xffff0000, v94
	v_pk_mul_f32 v[8:9], v[8:9], v[16:17]
	v_lshlrev_b32_e32 v16, 16, v95
	v_and_b32_e32 v17, 0xffff0000, v95
	v_lshlrev_b32_e32 v14, 16, v93
	v_and_b32_e32 v15, 0xffff0000, v93
	v_pk_mul_f32 v[10:11], v[10:11], v[16:17]
	v_lshl_add_u64 v[16:17], s[6:7], 0, v[20:21]
	v_pk_mul_f32 v[14:15], v[18:19], v[14:15]
	v_lshl_add_u64 v[16:17], v[16:17], 0, v[146:147]
	global_store_dwordx4 v[16:17], v[12:15], off
	global_store_dwordx4 v[16:17], v[8:11], off offset:16
	s_waitcnt vmcnt(14)
	s_nop 0
	v_lshlrev_b32_e32 v8, 16, v64
	v_and_b32_e32 v9, 0xffff0000, v64
	v_pk_mul_f32 v[4:5], v[4:5], v[8:9]
	v_lshlrev_b32_e32 v8, 16, v65
	v_and_b32_e32 v9, 0xffff0000, v65
	v_pk_mul_f32 v[6:7], v[6:7], v[8:9]
	v_lshlrev_b32_e32 v8, 16, v66
	v_and_b32_e32 v9, 0xffff0000, v66
	v_pk_mul_f32 v[0:1], v[0:1], v[8:9]
	v_lshlrev_b32_e32 v8, 16, v67
	v_and_b32_e32 v9, 0xffff0000, v67
	v_pk_mul_f32 v[2:3], v[2:3], v[8:9]
	global_store_dwordx4 v[16:17], v[4:7], off offset:512
	global_store_dwordx4 v[16:17], v[0:3], off offset:528
	s_cmp_eq_u32 s87, 1
	s_cbranch_scc0 .Lp3_early_done
	s_cmp_lg_u32 s64, 1
	s_cbranch_scc1 .Lp3_early_done
	s_waitcnt vmcnt(0)
	s_barrier
	v_cmp_eq_u32_e64 s[84:85], 0, v128
	s_and_saveexec_b64 s[88:89], s[84:85]
	s_cbranch_execz .Lp3_early_x
	buffer_wbl2 sc1
	s_waitcnt vmcnt(0)
	s_lshl_b32 s86, s34, 2
	v_mov_b32_e32 v252, s86
	v_mov_b32_e32 v253, 1
	global_atomic_add v252, v253, s[50:51]
.Lp3_early_x:
	s_or_b64 exec, exec, s[88:89]
.Lp3_early_done:
	s_cbranch_vccnz .LBB0_1386
	s_andn2_b64 vcc, exec, s[10:11]
	s_cbranch_vccnz .LBB0_1385
	s_barrier
	s_branch .LBB0_1385
